# a+b plus P7 fused-rmsnorm epilogue: the 8 serialised row-sum loads (global_load_dword sc1 + vmcnt(0) each) issued together at the top
# baseline (speedup 1.0000x reference)
;     __device__ __forceinline__ void operator()(f32x4 (&acc)[2][2][4][2], const Unit& u, int wr, int wc, int fr, int fq) const {
;     ...
;         const float qnan = __builtin_nanf("");
;         f32x4 gv[2][2];
; #pragma unroll
;         for (int bj = 0; bj < 2; ++bj) { gv[bj][0] = *(const f32x4*)(gfin + col0 + bj * HALF); gv[bj][1] = *(const f32x4*)(gfin + col0 + bj * HALF + 4); }
;         float rs[8];
; #pragma unroll
;         for (int g = 0; g < 8; ++g) { const float ss = __hip_atomic_load(rowss + row0 + (g >> 2) * HALF + (g & 3) * 16, __ATOMIC_RELAXED, __HIP_MEMORY_SCOPE_AGENT); rs[g] = dead ? qnan : 1.0f / sqrtf(ss * (1.0f / 4096.0f) + 1e-6f); }
.LBB0_1250:
	global_load_dwordx4 v[8:11], v[146:147], off offset:16
	global_load_dwordx4 v[12:15], v[146:147], off
	global_load_dwordx4 v[0:3], v[146:147], off offset:528
	global_load_dwordx4 v[4:7], v[146:147], off offset:512
	global_load_dword v81, v[162:163], off sc1
	global_load_dword v239, v[162:163], off offset:64 sc1
	global_load_dword v240, v[162:163], off offset:128 sc1
	global_load_dword v241, v[162:163], off offset:192 sc1
	global_load_dword v242, v[162:163], off offset:512 sc1
	global_load_dword v243, v[162:163], off offset:576 sc1
	global_load_dword v244, v[162:163], off offset:640 sc1
	global_load_dword v245, v[162:163], off offset:704 sc1
	v_mov_b32_e32 v80, 0x7fc00000
	s_and_b64 vcc, exec, s[6:7]
	v_mov_b32_e32 v164, 0x7fc00000
	s_cbranch_vccnz .LBB0_1252
	s_waitcnt vmcnt(0)
	v_fmamk_f32 v81, v81, 0x39800000, v181
	v_mul_f32_e32 v82, 0x4f800000, v81
	v_cmp_gt_f32_e32 vcc, s53, v81
	s_nop 1
	v_cndmask_b32_e32 v81, v81, v82, vcc
	v_sqrt_f32_e32 v82, v81
	s_nop 0
	v_add_u32_e32 v83, -1, v82
	v_fma_f32 v85, -v83, v82, v81
	v_add_u32_e32 v84, 1, v82
	v_cmp_ge_f32_e64 s[4:5], 0, v85
	s_nop 1
	v_cndmask_b32_e64 v83, v82, v83, s[4:5]
	v_fma_f32 v82, -v84, v82, v81
	v_cmp_lt_f32_e64 s[4:5], 0, v82
	s_nop 1
	v_cndmask_b32_e64 v82, v83, v84, s[4:5]
	v_mul_f32_e32 v83, 0x37800000, v82
	v_cndmask_b32_e32 v82, v82, v83, vcc
	v_cmp_class_f32_e32 vcc, v81, v182
	s_nop 1
	v_cndmask_b32_e32 v81, v82, v81, vcc
	v_div_scale_f32 v82, s[4:5], v81, v81, 1.0
	v_rcp_f32_e32 v83, v82
	s_nop 0
	v_fma_f32 v84, -v82, v83, 1.0
	v_fmac_f32_e32 v83, v84, v83
	v_div_scale_f32 v84, vcc, 1.0, v81, 1.0
	v_mul_f32_e32 v85, v84, v83
	v_fma_f32 v86, -v82, v85, v84
	v_fmac_f32_e32 v85, v86, v83
	v_fma_f32 v82, -v82, v85, v84
	v_div_fmas_f32 v82, v82, v83, v85
	v_div_fixup_f32 v164, v82, v81, 1.0
.LBB0_1252:
	s_xor_b64 s[6:7], s[6:7], -1
	v_cndmask_b32_e64 v82, 0, 1, s[6:7]
	v_cmp_ne_u32_e64 s[4:5], 1, v82
	s_andn2_b64 vcc, exec, s[6:7]
	s_cbranch_vccnz .LBB0_1254
	s_waitcnt vmcnt(0)
	v_fmamk_f32 v80, v239, 0x39800000, v181
	v_mul_f32_e32 v81, 0x4f800000, v80
	v_cmp_gt_f32_e32 vcc, s53, v80
	s_nop 1
	v_cndmask_b32_e32 v80, v80, v81, vcc
	v_sqrt_f32_e32 v81, v80
	s_nop 0
	v_add_u32_e32 v82, -1, v81
	v_fma_f32 v84, -v82, v81, v80
	v_add_u32_e32 v83, 1, v81
	v_cmp_ge_f32_e64 s[6:7], 0, v84
	s_nop 1
	v_cndmask_b32_e64 v82, v81, v82, s[6:7]
	v_fma_f32 v81, -v83, v81, v80
	v_cmp_lt_f32_e64 s[6:7], 0, v81
	s_nop 1
	v_cndmask_b32_e64 v81, v82, v83, s[6:7]
	v_mul_f32_e32 v82, 0x37800000, v81
	v_cndmask_b32_e32 v81, v81, v82, vcc
	v_cmp_class_f32_e32 vcc, v80, v182
	s_nop 1
	v_cndmask_b32_e32 v80, v81, v80, vcc
	v_div_scale_f32 v81, s[6:7], v80, v80, 1.0
	v_rcp_f32_e32 v82, v81
	s_nop 0
	v_fma_f32 v83, -v81, v82, 1.0
	v_fmac_f32_e32 v82, v83, v82
	v_div_scale_f32 v83, vcc, 1.0, v80, 1.0
	v_mul_f32_e32 v84, v83, v82
	v_fma_f32 v85, -v81, v84, v83
	v_fmac_f32_e32 v84, v85, v82
	v_fma_f32 v81, -v81, v84, v83
	v_div_fmas_f32 v81, v81, v82, v84
	v_div_fixup_f32 v80, v81, v80, 1.0
.LBB0_1254:
	v_mov_b32_e32 v82, 0x7fc00000
	s_and_b64 vcc, exec, s[4:5]
	v_mov_b32_e32 v166, 0x7fc00000
	s_cbranch_vccnz .LBB0_1256
	s_waitcnt vmcnt(0)
	v_fmamk_f32 v81, v240, 0x39800000, v181
	v_mul_f32_e32 v83, 0x4f800000, v81
	v_cmp_gt_f32_e32 vcc, s53, v81
	s_nop 1
	v_cndmask_b32_e32 v81, v81, v83, vcc
	v_sqrt_f32_e32 v83, v81
	s_nop 0
	v_add_u32_e32 v84, -1, v83
	v_fma_f32 v86, -v84, v83, v81
	v_add_u32_e32 v85, 1, v83
	v_cmp_ge_f32_e64 s[6:7], 0, v86
	s_nop 1
	v_cndmask_b32_e64 v84, v83, v84, s[6:7]
	v_fma_f32 v83, -v85, v83, v81
	v_cmp_lt_f32_e64 s[6:7], 0, v83
	s_nop 1
	v_cndmask_b32_e64 v83, v84, v85, s[6:7]
	v_mul_f32_e32 v84, 0x37800000, v83
	v_cndmask_b32_e32 v83, v83, v84, vcc
	v_cmp_class_f32_e32 vcc, v81, v182
	s_nop 1
	v_cndmask_b32_e32 v81, v83, v81, vcc
	v_div_scale_f32 v83, s[6:7], v81, v81, 1.0
	v_rcp_f32_e32 v84, v83
	s_nop 0
	v_fma_f32 v85, -v83, v84, 1.0
	v_fmac_f32_e32 v84, v85, v84
	v_div_scale_f32 v85, vcc, 1.0, v81, 1.0
	v_mul_f32_e32 v86, v85, v84
	v_fma_f32 v87, -v83, v86, v85
	v_fmac_f32_e32 v86, v87, v84
	v_fma_f32 v83, -v83, v86, v85
	v_div_fmas_f32 v83, v83, v84, v86
	v_div_fixup_f32 v166, v83, v81, 1.0
.LBB0_1256:
	s_and_b64 vcc, exec, s[4:5]
	s_cbranch_vccnz .LBB0_1258
	s_waitcnt vmcnt(0)
	v_fmamk_f32 v81, v241, 0x39800000, v181
	v_mul_f32_e32 v82, 0x4f800000, v81
	v_cmp_gt_f32_e32 vcc, s53, v81
	s_nop 1
	v_cndmask_b32_e32 v81, v81, v82, vcc
	v_sqrt_f32_e32 v82, v81
	s_nop 0
	v_add_u32_e32 v83, -1, v82
	v_fma_f32 v85, -v83, v82, v81
	v_add_u32_e32 v84, 1, v82
	v_cmp_ge_f32_e64 s[6:7], 0, v85
	s_nop 1
	v_cndmask_b32_e64 v83, v82, v83, s[6:7]
	v_fma_f32 v82, -v84, v82, v81
	v_cmp_lt_f32_e64 s[6:7], 0, v82
	s_nop 1
	v_cndmask_b32_e64 v82, v83, v84, s[6:7]
	v_mul_f32_e32 v83, 0x37800000, v82
	v_cndmask_b32_e32 v82, v82, v83, vcc
	v_cmp_class_f32_e32 vcc, v81, v182
	s_nop 1
	v_cndmask_b32_e32 v81, v82, v81, vcc
	v_div_scale_f32 v82, s[6:7], v81, v81, 1.0
	v_rcp_f32_e32 v83, v82
	s_nop 0
	v_fma_f32 v84, -v82, v83, 1.0
	v_fmac_f32_e32 v83, v84, v83
	v_div_scale_f32 v84, vcc, 1.0, v81, 1.0
	v_mul_f32_e32 v85, v84, v83
	v_fma_f32 v86, -v82, v85, v84
	v_fmac_f32_e32 v85, v86, v83
	v_fma_f32 v82, -v82, v85, v84
	v_div_fmas_f32 v82, v82, v83, v85
	v_div_fixup_f32 v82, v82, v81, 1.0
;     __device__ __forceinline__ void operator()(f32x4 (&acc)[2][2][4][2], const Unit& u, int wr, int wc, int fr, int fq) const {
;     ...
;         const float qnan = __builtin_nanf("");
;         f32x4 gv[2][2];
; #pragma unroll
;         for (int bj = 0; bj < 2; ++bj) { gv[bj][0] = *(const f32x4*)(gfin + col0 + bj * HALF); gv[bj][1] = *(const f32x4*)(gfin + col0 + bj * HALF + 4); }
;         float rs[8];
; #pragma unroll
;         for (int g = 0; g < 8; ++g) { const float ss = __hip_atomic_load(rowss + row0 + (g >> 2) * HALF + (g & 3) * 16, __ATOMIC_RELAXED, __HIP_MEMORY_SCOPE_AGENT); rs[g] = dead ? qnan : 1.0f / sqrtf(ss * (1.0f / 4096.0f) + 1e-6f); }
.LBB0_1258:
	v_mov_b32_e32 v84, 0x7fc00000
	s_and_b64 vcc, exec, s[4:5]
	v_mov_b32_e32 v168, 0x7fc00000
	s_cbranch_vccnz .LBB0_1260
	s_waitcnt vmcnt(0)
	v_fmamk_f32 v81, v242, 0x39800000, v181
	v_mul_f32_e32 v83, 0x4f800000, v81
	v_cmp_gt_f32_e32 vcc, s53, v81
	s_nop 1
	v_cndmask_b32_e32 v81, v81, v83, vcc
	v_sqrt_f32_e32 v83, v81
	s_nop 0
	v_add_u32_e32 v85, -1, v83
	v_fma_f32 v87, -v85, v83, v81
	v_add_u32_e32 v86, 1, v83
	v_cmp_ge_f32_e64 s[6:7], 0, v87
	s_nop 1
	v_cndmask_b32_e64 v85, v83, v85, s[6:7]
	v_fma_f32 v83, -v86, v83, v81
	v_cmp_lt_f32_e64 s[6:7], 0, v83
	s_nop 1
	v_cndmask_b32_e64 v83, v85, v86, s[6:7]
	v_mul_f32_e32 v85, 0x37800000, v83
	v_cndmask_b32_e32 v83, v83, v85, vcc
	v_cmp_class_f32_e32 vcc, v81, v182
	s_nop 1
	v_cndmask_b32_e32 v81, v83, v81, vcc
	v_div_scale_f32 v83, s[6:7], v81, v81, 1.0
	v_rcp_f32_e32 v85, v83
	s_nop 0
	v_fma_f32 v86, -v83, v85, 1.0
	v_fmac_f32_e32 v85, v86, v85
	v_div_scale_f32 v86, vcc, 1.0, v81, 1.0
	v_mul_f32_e32 v87, v86, v85
	v_fma_f32 v165, -v83, v87, v86
	v_fmac_f32_e32 v87, v165, v85
	v_fma_f32 v83, -v83, v87, v86
	v_div_fmas_f32 v83, v83, v85, v87
	v_div_fixup_f32 v168, v83, v81, 1.0
.LBB0_1260:
	s_and_b64 vcc, exec, s[4:5]
	s_cbranch_vccnz .LBB0_1262
	s_waitcnt vmcnt(0)
	v_fmamk_f32 v81, v243, 0x39800000, v181
	v_mul_f32_e32 v83, 0x4f800000, v81
	v_cmp_gt_f32_e32 vcc, s53, v81
	s_nop 1
	v_cndmask_b32_e32 v81, v81, v83, vcc
	v_sqrt_f32_e32 v83, v81
	s_nop 0
	v_add_u32_e32 v84, -1, v83
	v_fma_f32 v86, -v84, v83, v81
	v_add_u32_e32 v85, 1, v83
	v_cmp_ge_f32_e64 s[6:7], 0, v86
	s_nop 1
	v_cndmask_b32_e64 v84, v83, v84, s[6:7]
	v_fma_f32 v83, -v85, v83, v81
	v_cmp_lt_f32_e64 s[6:7], 0, v83
	s_nop 1
	v_cndmask_b32_e64 v83, v84, v85, s[6:7]
	v_mul_f32_e32 v84, 0x37800000, v83
	v_cndmask_b32_e32 v83, v83, v84, vcc
	v_cmp_class_f32_e32 vcc, v81, v182
	s_nop 1
	v_cndmask_b32_e32 v81, v83, v81, vcc
	v_div_scale_f32 v83, s[6:7], v81, v81, 1.0
	v_rcp_f32_e32 v84, v83
	s_nop 0
	v_fma_f32 v85, -v83, v84, 1.0
	v_fmac_f32_e32 v84, v85, v84
	v_div_scale_f32 v85, vcc, 1.0, v81, 1.0
	v_mul_f32_e32 v86, v85, v84
	v_fma_f32 v87, -v83, v86, v85
	v_fmac_f32_e32 v86, v87, v84
	v_fma_f32 v83, -v83, v86, v85
	v_div_fmas_f32 v83, v83, v84, v86
	v_div_fixup_f32 v84, v83, v81, 1.0
.LBB0_1262:
	v_mov_b32_e32 v86, 0x7fc00000
	s_and_b64 vcc, exec, s[4:5]
	v_mov_b32_e32 v170, 0x7fc00000
	s_cbranch_vccnz .LBB0_1264
	s_waitcnt vmcnt(0)
	v_fmamk_f32 v81, v244, 0x39800000, v181
	v_mul_f32_e32 v83, 0x4f800000, v81
	v_cmp_gt_f32_e32 vcc, s53, v81
	s_nop 1
	v_cndmask_b32_e32 v81, v81, v83, vcc
	v_sqrt_f32_e32 v83, v81
	s_nop 0
	v_add_u32_e32 v85, -1, v83
	v_fma_f32 v165, -v85, v83, v81
	v_add_u32_e32 v87, 1, v83
	v_cmp_ge_f32_e64 s[6:7], 0, v165
	s_nop 1
	v_cndmask_b32_e64 v85, v83, v85, s[6:7]
	v_fma_f32 v83, -v87, v83, v81
	v_cmp_lt_f32_e64 s[6:7], 0, v83
	s_nop 1
	v_cndmask_b32_e64 v83, v85, v87, s[6:7]
	v_mul_f32_e32 v85, 0x37800000, v83
	v_cndmask_b32_e32 v83, v83, v85, vcc
	v_cmp_class_f32_e32 vcc, v81, v182
	s_nop 1
	v_cndmask_b32_e32 v81, v83, v81, vcc
	v_div_scale_f32 v83, s[6:7], v81, v81, 1.0
	v_rcp_f32_e32 v85, v83
	s_nop 0
	v_fma_f32 v87, -v83, v85, 1.0
	v_fmac_f32_e32 v85, v87, v85
	v_div_scale_f32 v87, vcc, 1.0, v81, 1.0
	v_mul_f32_e32 v165, v87, v85
	v_fma_f32 v170, -v83, v165, v87
	v_fmac_f32_e32 v165, v170, v85
	v_fma_f32 v83, -v83, v165, v87
	v_div_fmas_f32 v83, v83, v85, v165
	v_div_fixup_f32 v170, v83, v81, 1.0
.LBB0_1264:
	s_and_b64 vcc, exec, s[4:5]
	s_cbranch_vccnz .LBB0_1266
	s_waitcnt vmcnt(0)
	v_fmamk_f32 v81, v245, 0x39800000, v181
	v_mul_f32_e32 v83, 0x4f800000, v81
	v_cmp_gt_f32_e32 vcc, s53, v81
	s_nop 1
	v_cndmask_b32_e32 v81, v81, v83, vcc
	v_sqrt_f32_e32 v83, v81
	s_nop 0
	v_add_u32_e32 v85, -1, v83
	v_fma_f32 v87, -v85, v83, v81
	v_add_u32_e32 v86, 1, v83
	v_cmp_ge_f32_e64 s[4:5], 0, v87
	s_nop 1
	v_cndmask_b32_e64 v85, v83, v85, s[4:5]
	v_fma_f32 v83, -v86, v83, v81
	v_cmp_lt_f32_e64 s[4:5], 0, v83
	s_nop 1
	v_cndmask_b32_e64 v83, v85, v86, s[4:5]
	v_mul_f32_e32 v85, 0x37800000, v83
	v_cndmask_b32_e32 v83, v83, v85, vcc
	v_cmp_class_f32_e32 vcc, v81, v182
	s_nop 1
	v_cndmask_b32_e32 v81, v83, v81, vcc
	v_div_scale_f32 v83, s[4:5], v81, v81, 1.0
	v_rcp_f32_e32 v85, v83
	s_nop 0
	v_fma_f32 v86, -v83, v85, 1.0
	v_fmac_f32_e32 v85, v86, v85
	v_div_scale_f32 v86, vcc, 1.0, v81, 1.0
	v_mul_f32_e32 v87, v86, v85
	v_fma_f32 v162, -v83, v87, v86
	v_fmac_f32_e32 v87, v162, v85
	v_fma_f32 v83, -v83, v87, v86
	v_div_fmas_f32 v83, v83, v85, v87
	v_div_fixup_f32 v86, v83, v81, 1.0
